# AA: P0 split - transposes, early global barrier, XCD group B does its deferred-transpose share, then x rows partitioned per batch/XCD with an XCD-local barrier before P1
# baseline (speedup 1.0000x reference)
_Z8skel_fwd4Args:
	s_mov_b32 s99, 0
	s_mov_b32 s98, 0
	s_load_dwordx8 s[68:75], s[0:1], 0x80
	s_load_dword s3, s[0:1], 0xb0
	s_load_dwordx2 s[76:77], s[0:1], 0xa0
	s_load_dword s4, s[0:1], 0xa8
	v_mov_b32_e32 v3, 0
	v_and_b32_e32 v1, 0x3ff, v0
	s_add_u32 s6, s0, 0xb0
	v_readfirstlane_b32 s33, v1
	v_mbcnt_lo_u32_b32 v3, -1, v3
	s_addc_u32 s7, s1, 0
	s_andn2_b32 s33, s33, 63
	v_mbcnt_hi_u32_b32 v3, -1, v3
	v_add_u32_e32 v3, s33, v3
	s_waitcnt lgkmcnt(0)
	v_writelane_b32 v255, s4, 0
	v_writelane_b32 v255, s0, 32
	v_writelane_b32 v255, s1, 33
	v_mov_b32_e32 v2, 0
	s_nop 0
	v_cmp_eq_u32_e32 vcc, 0, v3
	s_and_saveexec_b64 s[4:5], vcc
	s_cbranch_execz .LBB0_3
	s_add_i32 s10, 0, 0x25fd0
	v_mov_b32_e32 v3, s10
	s_add_i32 s10, 0, 0x25fd4
	s_mov_b64 s[8:9], exec
	ds_write_b32 v3, v2
	v_mov_b32_e32 v3, s10
	ds_write_b32 v3, v2
	v_mbcnt_lo_u32_b32 v2, s8, 0
	v_mbcnt_hi_u32_b32 v2, s9, v2
	v_cmp_eq_u32_e32 vcc, 0, v2
	s_getreg_b32 s10, hwreg(HW_REG_XCC_ID, 0, 4)
	s_and_b64 s[12:13], exec, vcc
	s_mov_b64 exec, s[12:13]
	s_cbranch_execz .LBB0_3
	s_and_b32 s101, s10, 15
	s_add_i32 s101, s101, 1
	s_lshl_b32 s100, s2, 2
	s_add_i32 s100, s100, 0xe000
	v_mov_b32_e32 v4, s100
	v_mov_b32_e32 v5, s101
	global_atomic_add v4, v5, s[76:77]
	s_lshl_b32 s10, s10, 8
	s_and_b32 s10, s10, 0xf00
	s_add_u32 s10, s76, s10
	s_addc_u32 s11, s77, 0
	s_bcnt1_i32_b64 s8, s[8:9]
	v_mov_b32_e32 v2, 0x8000
	v_mov_b32_e32 v3, s8
	global_atomic_add v2, v3, s[10:11] offset:1024

.Lp0_b1:
	s_bitcmp1_b32 s99, 7
	s_cbranch_scc0 .Lp0_b2
	s_mov_b32 s101, -1

.LBB0_53:
	s_bitcmp1_b32 s99, 2
	s_cbranch_scc1 .LBB0_65
	s_bitcmp1_b32 s99, 7
	s_cbranch_scc0 .Lg0_entry
	s_mov_b32 s101, 0x8000
	s_cmp_lg_u32 s3, 0x100
	s_cbranch_scc1 .Lrows_go
	s_and_b32 s20, s2, 7
	s_add_i32 s101, s20, 1
	s_lshl_b32 s101, s101, 12
	s_lshl_b32 s20, s20, 12
	s_lshr_b32 s78, s2, 3
	s_lshl_b32 s78, s78, 3
	s_add_i32 s20, s20, s78
	s_lshr_b32 s78, s33, 6
	s_add_i32 s20, s20, s78
	s_movk_i32 s78, 0x100

.LBB0_56:
	s_or_b64 exec, exec, s[0:1]
	s_cmp_lt_i32 s20, s101
	s_waitcnt lgkmcnt(0)
	s_barrier
	s_cbranch_scc0 .LBB0_65
	s_add_u32 s22, s76, 0x2440000
	s_addc_u32 s23, s77, 0
	s_add_i32 s0, s78, s20
	s_cmp_lt_i32 s0, s101
	s_cselect_b32 s0, s0, 0
	s_ashr_i32 s1, s0, 31
	s_lshl_b64 s[0:1], s[0:1], 12
	s_add_u32 s0, s36, s0
	v_lshlrev_b32_e32 v18, 4, v193
	s_addc_u32 s1, s37, s1
	s_ashr_i32 s21, s20, 31
	global_load_dwordx4 v[0:3], v18, s[0:1] offset:3072 nt
	global_load_dwordx4 v[4:7], v18, s[0:1] offset:2048 nt
	global_load_dwordx4 v[8:11], v18, s[0:1] offset:1024 nt
	global_load_dwordx4 v[12:15], v18, s[0:1] nt
	s_lshl_b64 s[0:1], s[20:21], 12
	s_add_u32 s0, s36, s0
	s_addc_u32 s1, s37, s1
	global_load_dwordx4 v[160:163], v18, s[0:1] offset:3072 nt
	global_load_dwordx4 v[164:167], v18, s[0:1] offset:2048 nt
	global_load_dwordx4 v[168:171], v18, s[0:1] offset:1024 nt
	global_load_dwordx4 v[172:175], v18, s[0:1] nt
	v_mov_b32_e32 v19, 0
	v_lshl_add_u64 v[176:177], s[36:37], 0, v[18:19]
	v_mov_b32_e32 v17, v19
	v_lshlrev_b32_e32 v18, 2, v193
	v_lshl_add_u32 v140, v193, 5, 0
	v_lshl_add_u64 v[178:179], s[34:35], 0, v[16:17]
	v_lshl_add_u64 v[180:181], s[48:49], 0, v[18:19]
	ds_read_b128 v[16:19], v140
	ds_read_b128 v[20:23], v140 offset:16
	ds_read_b128 v[24:27], v140 offset:2048
	ds_read_b128 v[28:31], v140 offset:2064
	ds_read_b128 v[32:35], v140 offset:4096
	ds_read_b128 v[36:39], v140 offset:4112
	ds_read_b128 v[40:43], v140 offset:6144
	ds_read_b128 v[44:47], v140 offset:6160
	ds_read_b128 v[48:51], v140 offset:8192
	ds_read_b128 v[52:55], v140 offset:8208
	ds_read_b128 v[56:59], v140 offset:10240
	ds_read_b128 v[60:63], v140 offset:10256
	ds_read_b128 v[64:67], v140 offset:12288
	ds_read_b128 v[68:71], v140 offset:12304
	ds_read_b128 v[72:75], v140 offset:14336
	ds_read_b128 v[76:79], v140 offset:14352
	ds_read_b128 v[80:83], v140 offset:16384
	ds_read_b128 v[84:87], v140 offset:16400
	ds_read_b128 v[88:91], v140 offset:18432
	ds_read_b128 v[92:95], v140 offset:18448
	ds_read_b128 v[96:99], v140 offset:20480
	ds_read_b128 v[100:103], v140 offset:20496
	ds_read_b128 v[104:107], v140 offset:22528
	ds_read_b128 v[108:111], v140 offset:22544
	ds_read_b128 v[112:115], v140 offset:24576
	ds_read_b128 v[116:119], v140 offset:24592
	ds_read_b128 v[120:123], v140 offset:26624
	ds_read_b128 v[124:127], v140 offset:26640
	ds_read_b128 v[128:131], v140 offset:28672
	ds_read_b128 v[132:135], v140 offset:28688
	ds_read_b128 v[136:139], v140 offset:30720
	ds_read_b128 v[140:143], v140 offset:30736
	s_mov_b32 s25, 0
	s_lshl_b32 s58, s78, 1
	v_cmp_gt_u32_e64 s[0:1], 8, v193
	v_cmp_eq_u32_e64 s[16:17], 1, v193
	v_cmp_eq_u32_e64 s[4:5], 2, v193
	v_cmp_eq_u32_e64 s[6:7], 3, v193
	v_cmp_eq_u32_e64 s[8:9], 4, v193
	v_cmp_eq_u32_e64 s[10:11], 5, v193
	v_cmp_eq_u32_e64 s[12:13], 6, v193
	v_cmp_eq_u32_e64 s[14:15], 7, v193
	v_mov_b32_e32 v194, 0x358637bd
	s_mov_b32 s59, 0xf800000
	v_mov_b32_e32 v195, 0x260
	s_mov_b32 s60, 0xbfb8aa3b
	s_mov_b32 s61, 0x42ce8ed0
	s_mov_b32 s62, 0xc2b17218
	s_mov_b32 s63, 0x7f800000
	s_mov_b32 s64, 0x3f2aaaab
	v_mov_b32_e32 v196, 0x3ecc95a3
	s_mov_b32 s65, 0x3f317218
	s_mov_b32 s66, 0x33800000
	s_mov_b32 s67, 0x3fb8aa3b
	s_mov_b32 s68, 0xc2ce8ed0
	s_mov_b32 s69, 0x42b17218
	v_mov_b32_e32 v197, 0x7f800000
	v_mov_b32_e32 v182, 0x3f317218
	s_branch .LBB0_60

.LBB0_59:
	s_or_b64 exec, exec, s[18:19]
	v_mov_b64_e32 v[162:163], v[2:3]
	v_mov_b64_e32 v[166:167], v[6:7]
	v_mov_b64_e32 v[170:171], v[10:11]
	v_mov_b64_e32 v[174:175], v[14:15]
	s_sub_i32 s20, s70, s78
	v_mov_b64_e32 v[160:161], v[0:1]
	v_mov_b64_e32 v[164:165], v[4:5]
	v_mov_b64_e32 v[168:169], v[8:9]
	v_mov_b64_e32 v[172:173], v[12:13]
	s_waitcnt vmcnt(4)
	v_mov_b64_e32 v[0:1], v[156:157]
	v_mov_b64_e32 v[4:5], v[152:153]
	v_mov_b64_e32 v[8:9], v[148:149]
	v_mov_b64_e32 v[12:13], v[144:145]
	s_cmp_ge_i32 s20, s101
	v_mov_b64_e32 v[2:3], v[158:159]
	v_mov_b64_e32 v[6:7], v[154:155]
	v_mov_b64_e32 v[10:11], v[150:151]
	v_mov_b64_e32 v[14:15], v[146:147]
	s_cbranch_scc1 .LBB0_65
.LBB0_60:
	s_add_i32 s70, s20, s58
	s_cmp_lt_i32 s70, s101
	s_cselect_b32 s18, s70, s20
	s_ashr_i32 s19, s18, 31
	s_lshl_b64 s[18:19], s[18:19], 12
	v_lshl_add_u64 v[156:157], v[176:177], 0, s[18:19]
	global_load_dwordx4 v[144:147], v[156:157], off nt
	global_load_dwordx4 v[148:151], v[156:157], off offset:1024 nt
	global_load_dwordx4 v[152:155], v[156:157], off offset:2048 nt
	s_nop 0
	global_load_dwordx4 v[156:159], v[156:157], off offset:3072 nt
	s_waitcnt vmcnt(4) lgkmcnt(14)
	v_fma_f32 v183, v172, v16, 0
	v_fmac_f32_e32 v183, v173, v24
	v_fmac_f32_e32 v183, v174, v32
	v_fmac_f32_e32 v183, v175, v40
	v_pk_mul_f32 v[184:185], v[170:171], v[170:171]
	v_pk_mul_f32 v[186:187], v[168:169], v[168:169]
	v_fma_f32 v205, v172, v17, 0
	v_fmac_f32_e32 v183, v168, v48
	v_pk_mov_b32 v[188:189], v[186:187], v[184:185] op_sel:[1,0]
	v_mov_b32_e32 v187, v185
	v_fmac_f32_e32 v205, v173, v25
	v_fmac_f32_e32 v183, v169, v56
	v_pk_add_f32 v[184:185], v[188:189], v[186:187]
	v_fmac_f32_e32 v205, v174, v33
	v_fmac_f32_e32 v183, v170, v64
	v_pk_add_f32 v[184:185], v[184:185], v[184:185] op_sel_hi:[0,1]
	v_fmac_f32_e32 v205, v175, v41
	v_fmac_f32_e32 v183, v171, v72
	v_pk_mul_f32 v[198:199], v[174:175], v[174:175]
	v_pk_mul_f32 v[200:201], v[172:173], v[172:173]
	v_mul_f32_e32 v184, v164, v164
	v_fma_f32 v207, v172, v18, 0
	v_fmac_f32_e32 v205, v168, v49
	v_fmac_f32_e32 v183, v164, v80
	v_pk_mov_b32 v[202:203], v[200:201], v[198:199] op_sel:[1,0]
	v_mov_b32_e32 v201, v199
	v_pk_fma_f32 v[186:187], v[164:165], v[164:165], v[184:185] op_sel_hi:[1,1,0]
	v_mul_f32_e32 v184, v166, v166
	v_fmac_f32_e32 v207, v173, v26
	v_fmac_f32_e32 v205, v169, v57
	s_waitcnt lgkmcnt(13)
	v_fmac_f32_e32 v183, v165, v88
	v_pk_add_f32 v[198:199], v[202:203], v[200:201]
	v_pk_fma_f32 v[190:191], v[166:167], v[166:167], v[184:185] op_sel_hi:[1,1,0]
	v_fmac_f32_e32 v207, v174, v34
	v_fmac_f32_e32 v205, v170, v65
	s_waitcnt lgkmcnt(11)
	v_fmac_f32_e32 v183, v166, v96
	v_pk_add_f32 v[198:199], v[198:199], v[198:199] op_sel_hi:[0,1]
	v_mul_f32_e32 v186, v160, v160
	v_mul_f32_e32 v190, v161, v161
	v_mul_f32_e32 v184, v162, v162
	v_mul_f32_e32 v188, v163, v163
	v_fmac_f32_e32 v207, v175, v42
	v_fmac_f32_e32 v205, v171, v73
	s_waitcnt lgkmcnt(9)
	v_fmac_f32_e32 v183, v167, v104
	v_mov_b32_e32 v189, v199
	v_fma_f32 v209, v172, v19, 0
	v_fmac_f32_e32 v207, v168, v50
	v_fmac_f32_e32 v205, v164, v81
	s_waitcnt lgkmcnt(7)
	v_fmac_f32_e32 v183, v160, v112
	v_pk_add_f32 v[186:187], v[186:187], v[190:191]
	v_pk_add_f32 v[184:185], v[184:185], v[188:189]
	v_fmac_f32_e32 v209, v173, v27
	v_fmac_f32_e32 v207, v169, v58
	v_fmac_f32_e32 v205, v165, v89
	s_waitcnt lgkmcnt(5)
	v_fmac_f32_e32 v183, v161, v120
	v_pk_add_f32 v[184:185], v[186:187], v[184:185]
	v_fmac_f32_e32 v209, v174, v35
	v_fmac_f32_e32 v207, v170, v66
	v_fmac_f32_e32 v205, v166, v97
	s_waitcnt lgkmcnt(3)
	v_fmac_f32_e32 v183, v162, v128
	v_add_f32_e32 v184, v184, v185
	v_fmac_f32_e32 v209, v175, v43
	v_fmac_f32_e32 v207, v171, v74
	v_fmac_f32_e32 v205, v167, v105
	s_waitcnt lgkmcnt(1)
	v_fmac_f32_e32 v183, v163, v136
	v_add_f32_dpp v184, v184, v184 row_ror:8 row_mask:0xf bank_mask:0xf bound_ctrl:1
	v_fma_f32 v204, v172, v20, 0
	v_fmac_f32_e32 v209, v168, v51
	v_fmac_f32_e32 v207, v164, v82
	v_fmac_f32_e32 v205, v160, v113
	v_add_f32_dpp v184, v184, v184 row_ror:4 row_mask:0xf bank_mask:0xf bound_ctrl:1
	v_add_f32_dpp v183, v183, v183 row_ror:8 row_mask:0xf bank_mask:0xf bound_ctrl:1
	v_fmac_f32_e32 v204, v173, v28
	v_fmac_f32_e32 v209, v169, v59
	v_fmac_f32_e32 v207, v165, v90
	v_fmac_f32_e32 v205, v161, v121
	v_add_f32_dpp v184, v184, v184 row_ror:2 row_mask:0xf bank_mask:0xf bound_ctrl:1
	v_add_f32_dpp v183, v183, v183 row_ror:4 row_mask:0xf bank_mask:0xf bound_ctrl:1
	v_fmac_f32_e32 v204, v174, v36
	v_fmac_f32_e32 v209, v170, v67
	v_fmac_f32_e32 v207, v166, v98
	v_fmac_f32_e32 v205, v162, v129
	v_add_f32_dpp v184, v184, v184 row_ror:1 row_mask:0xf bank_mask:0xf bound_ctrl:1
	v_add_f32_dpp v183, v183, v183 row_ror:2 row_mask:0xf bank_mask:0xf bound_ctrl:1
	v_fmac_f32_e32 v204, v175, v44
	v_fmac_f32_e32 v209, v171, v75
	v_fmac_f32_e32 v207, v167, v106
	v_fmac_f32_e32 v205, v163, v137
	v_readlane_b32 s24, v184, 48
	v_add_f32_dpp v183, v183, v183 row_ror:1 row_mask:0xf bank_mask:0xf bound_ctrl:1
	v_fma_f32 v206, v172, v21, 0
	v_fmac_f32_e32 v204, v168, v52
	v_fmac_f32_e32 v209, v164, v83
	v_fmac_f32_e32 v207, v160, v114
	v_mov_b32_e32 v185, s24
	v_readlane_b32 s26, v183, 0
	v_readlane_b32 s24, v183, 16
	v_readlane_b32 s27, v183, 32
	v_readlane_b32 s71, v183, 48
	v_add_f32_dpp v183, v205, v205 row_ror:8 row_mask:0xf bank_mask:0xf bound_ctrl:1
	v_fmac_f32_e32 v206, v173, v29
	v_fmac_f32_e32 v204, v169, v60
	v_fmac_f32_e32 v209, v165, v91
	v_fmac_f32_e32 v207, v161, v122
	v_add_f32_dpp v183, v183, v183 row_ror:4 row_mask:0xf bank_mask:0xf bound_ctrl:1
	v_fmac_f32_e32 v206, v174, v37
	v_fmac_f32_e32 v204, v170, v68
	v_fmac_f32_e32 v209, v166, v99
	v_fmac_f32_e32 v207, v162, v130
	v_add_f32_dpp v183, v183, v183 row_ror:2 row_mask:0xf bank_mask:0xf bound_ctrl:1
	v_fmac_f32_e32 v206, v175, v45
	v_fmac_f32_e32 v204, v171, v76
	v_fmac_f32_e32 v209, v167, v107
	v_fmac_f32_e32 v207, v163, v138
	v_readlane_b32 s21, v184, 16
	v_add_f32_dpp v183, v183, v183 row_ror:1 row_mask:0xf bank_mask:0xf bound_ctrl:1
	v_fma_f32 v208, v172, v22, 0
	v_fmac_f32_e32 v206, v168, v53
	v_fmac_f32_e32 v204, v164, v84
	v_fmac_f32_e32 v209, v160, v115
	v_readlane_b32 s18, v184, 0
	v_readlane_b32 s19, v184, 32
	v_mov_b32_e32 v184, s21
	v_readlane_b32 s28, v183, 0
	v_readlane_b32 s72, v183, 16
	v_readlane_b32 s29, v183, 32
	v_readlane_b32 s73, v183, 48
	v_add_f32_dpp v183, v207, v207 row_ror:8 row_mask:0xf bank_mask:0xf bound_ctrl:1
	v_fmac_f32_e32 v208, v173, v30
	v_fmac_f32_e32 v206, v169, v61
	v_fmac_f32_e32 v204, v165, v92
	v_fmac_f32_e32 v209, v161, v123
	v_pk_add_f32 v[184:185], s[18:19], v[184:185]
	v_add_f32_dpp v183, v183, v183 row_ror:4 row_mask:0xf bank_mask:0xf bound_ctrl:1
	v_fmac_f32_e32 v208, v174, v38
	v_fmac_f32_e32 v206, v170, v69
	v_fmac_f32_e32 v204, v166, v100
	v_fmac_f32_e32 v209, v162, v131
	v_add_f32_e32 v184, v184, v185
	v_add_f32_dpp v183, v183, v183 row_ror:2 row_mask:0xf bank_mask:0xf bound_ctrl:1
	v_fmac_f32_e32 v208, v175, v46
	v_fmac_f32_e32 v206, v171, v77
	v_fmac_f32_e32 v204, v167, v108
	v_fmamk_f32 v184, v184, 0x3a800000, v194
	v_fmac_f32_e32 v209, v163, v139
	v_add_f32_dpp v183, v183, v183 row_ror:1 row_mask:0xf bank_mask:0xf bound_ctrl:1
	v_fma_f32 v210, v172, v23, 0
	v_fmac_f32_e32 v208, v168, v54
	v_fmac_f32_e32 v206, v164, v85
	v_fmac_f32_e32 v204, v160, v116
	v_mul_f32_e32 v185, 0x4f800000, v184
	v_cmp_gt_f32_e32 vcc, s59, v184
	v_readlane_b32 s30, v183, 0
	v_readlane_b32 s79, v183, 16
	v_readlane_b32 s31, v183, 32
	v_readlane_b32 s80, v183, 48
	v_add_f32_dpp v183, v209, v209 row_ror:8 row_mask:0xf bank_mask:0xf bound_ctrl:1
	v_fmac_f32_e32 v210, v173, v31
	v_fmac_f32_e32 v208, v169, v62
	v_fmac_f32_e32 v206, v165, v93
	v_fmac_f32_e32 v204, v161, v124
	v_cndmask_b32_e32 v184, v184, v185, vcc
	v_add_f32_dpp v183, v183, v183 row_ror:4 row_mask:0xf bank_mask:0xf bound_ctrl:1
	v_fmac_f32_e32 v210, v174, v39
	v_fmac_f32_e32 v208, v170, v70
	v_fmac_f32_e32 v206, v166, v101
	v_fmac_f32_e32 v204, v162, v132
	v_sqrt_f32_e32 v185, v184
	v_add_f32_dpp v183, v183, v183 row_ror:2 row_mask:0xf bank_mask:0xf bound_ctrl:1
	v_fmac_f32_e32 v210, v175, v47
	v_fmac_f32_e32 v208, v171, v78
	v_fmac_f32_e32 v206, v167, v109
	s_waitcnt lgkmcnt(0)
	v_fmac_f32_e32 v204, v163, v140
	v_add_f32_dpp v183, v183, v183 row_ror:1 row_mask:0xf bank_mask:0xf bound_ctrl:1
	v_fmac_f32_e32 v210, v168, v55
	v_fmac_f32_e32 v208, v164, v86
	v_fmac_f32_e32 v206, v160, v117
	v_readlane_b32 s40, v183, 0
	v_readlane_b32 s81, v183, 16
	v_readlane_b32 s41, v183, 32
	v_readlane_b32 s82, v183, 48
	v_add_f32_dpp v183, v204, v204 row_ror:8 row_mask:0xf bank_mask:0xf bound_ctrl:1
	v_fmac_f32_e32 v210, v169, v63
	v_fmac_f32_e32 v208, v165, v94
	v_fmac_f32_e32 v206, v161, v125
	v_add_f32_dpp v183, v183, v183 row_ror:4 row_mask:0xf bank_mask:0xf bound_ctrl:1
	v_fmac_f32_e32 v210, v170, v71
	v_fmac_f32_e32 v208, v166, v102
	v_fmac_f32_e32 v206, v162, v133
	v_add_u32_e32 v186, -1, v185
	v_add_f32_dpp v183, v183, v183 row_ror:2 row_mask:0xf bank_mask:0xf bound_ctrl:1
	v_fmac_f32_e32 v210, v171, v79
	v_fmac_f32_e32 v208, v167, v110
	v_fmac_f32_e32 v206, v163, v141
	v_fma_f32 v187, -v186, v185, v184
	v_add_f32_dpp v183, v183, v183 row_ror:1 row_mask:0xf bank_mask:0xf bound_ctrl:1
	v_fmac_f32_e32 v210, v164, v87
	v_fmac_f32_e32 v208, v160, v118
	v_cmp_ge_f32_e64 s[18:19], 0, v187
	v_add_u32_e32 v187, 1, v185
	v_readlane_b32 s42, v183, 0
	v_readlane_b32 s83, v183, 16
	v_readlane_b32 s43, v183, 32
	v_readlane_b32 s84, v183, 48
	v_add_f32_dpp v183, v206, v206 row_ror:8 row_mask:0xf bank_mask:0xf bound_ctrl:1
	v_fmac_f32_e32 v210, v165, v95
	v_fmac_f32_e32 v208, v161, v126
	v_cndmask_b32_e64 v186, v185, v186, s[18:19]
	v_fma_f32 v185, -v187, v185, v184
	v_add_f32_dpp v183, v183, v183 row_ror:4 row_mask:0xf bank_mask:0xf bound_ctrl:1
	v_fmac_f32_e32 v210, v166, v103
	v_fmac_f32_e32 v208, v162, v134
	v_cmp_lt_f32_e64 s[18:19], 0, v185
	v_add_f32_dpp v183, v183, v183 row_ror:2 row_mask:0xf bank_mask:0xf bound_ctrl:1
	v_fmac_f32_e32 v210, v167, v111
	v_fmac_f32_e32 v208, v163, v142
	v_cndmask_b32_e64 v185, v186, v187, s[18:19]
	v_add_f32_dpp v183, v183, v183 row_ror:1 row_mask:0xf bank_mask:0xf bound_ctrl:1
	v_fmac_f32_e32 v210, v160, v119
	v_mul_f32_e32 v186, 0x37800000, v185
	v_readlane_b32 s48, v183, 0
	v_readlane_b32 s85, v183, 16
	v_readlane_b32 s49, v183, 32
	v_readlane_b32 s86, v183, 48
	v_add_f32_dpp v183, v208, v208 row_ror:8 row_mask:0xf bank_mask:0xf bound_ctrl:1
	v_fmac_f32_e32 v210, v161, v127
	v_cndmask_b32_e32 v185, v185, v186, vcc
	v_cmp_class_f32_e32 vcc, v184, v195
	v_add_f32_dpp v183, v183, v183 row_ror:4 row_mask:0xf bank_mask:0xf bound_ctrl:1
	v_fmac_f32_e32 v210, v162, v135
	v_cndmask_b32_e32 v184, v185, v184, vcc
	v_add_f32_dpp v183, v183, v183 row_ror:2 row_mask:0xf bank_mask:0xf bound_ctrl:1
	v_fmac_f32_e32 v210, v163, v143
	v_div_scale_f32 v185, s[18:19], v184, v184, 1.0
	v_add_f32_dpp v183, v183, v183 row_ror:1 row_mask:0xf bank_mask:0xf bound_ctrl:1
	v_rcp_f32_e32 v186, v185
	v_readlane_b32 s54, v183, 0
	v_readlane_b32 s87, v183, 16
	v_readlane_b32 s55, v183, 32
	v_readlane_b32 s88, v183, 48
	v_add_f32_dpp v183, v210, v210 row_ror:8 row_mask:0xf bank_mask:0xf bound_ctrl:1
	s_ashr_i32 s21, s20, 31
	s_lshl_b64 s[18:19], s[20:21], 11
	v_add_f32_dpp v183, v183, v183 row_ror:4 row_mask:0xf bank_mask:0xf bound_ctrl:1
	s_nop 1
	v_add_f32_dpp v183, v183, v183 row_ror:2 row_mask:0xf bank_mask:0xf bound_ctrl:1
	s_nop 1
	v_add_f32_dpp v183, v183, v183 row_ror:1 row_mask:0xf bank_mask:0xf bound_ctrl:1
	s_nop 0
	v_readlane_b32 s56, v183, 0
	v_readlane_b32 s89, v183, 16
	v_readlane_b32 s57, v183, 32
	v_readlane_b32 s90, v183, 48
	v_fma_f32 v183, -v185, v186, 1.0
	v_fmac_f32_e32 v186, v183, v186
	v_div_scale_f32 v183, vcc, 1.0, v184, 1.0
	v_mul_f32_e32 v187, v183, v186
	v_fma_f32 v188, -v185, v187, v183
	v_fmac_f32_e32 v187, v188, v186
	v_fma_f32 v183, -v185, v187, v183
	v_div_fmas_f32 v183, v183, v186, v187
	v_div_fixup_f32 v184, v183, v184, 1.0
	v_pk_mul_f32 v[172:173], v[172:173], v[184:185] op_sel_hi:[1,0]
	v_pk_mul_f32 v[174:175], v[174:175], v[184:185] op_sel_hi:[1,0]
	v_pk_mul_f32 v[168:169], v[168:169], v[184:185] op_sel_hi:[1,0]
	v_pk_mul_f32 v[170:171], v[170:171], v[184:185] op_sel_hi:[1,0]
	v_pk_mul_f32 v[164:165], v[164:165], v[184:185] op_sel_hi:[1,0]
	v_pk_mul_f32 v[166:167], v[166:167], v[184:185] op_sel_hi:[1,0]
	v_pk_mul_f32 v[160:161], v[160:161], v[184:185] op_sel_hi:[1,0]
	v_pk_mul_f32 v[162:163], v[162:163], v[184:185] op_sel_hi:[1,0]
	v_lshl_add_u64 v[186:187], v[178:179], 0, s[18:19]
	v_cvt_pk_bf16_f32 v172, v172, v173
	v_cvt_pk_bf16_f32 v173, v174, v175
	v_cvt_pk_bf16_f32 v168, v168, v169
	v_cvt_pk_bf16_f32 v169, v170, v171
	v_cvt_pk_bf16_f32 v164, v164, v165
	v_cvt_pk_bf16_f32 v165, v166, v167
	v_cvt_pk_bf16_f32 v160, v160, v161
	v_cvt_pk_bf16_f32 v161, v162, v163
	global_store_dwordx2 v[186:187], v[172:173], off sc0 sc1
	global_store_dwordx2 v[186:187], v[168:169], off offset:512 sc0 sc1
	global_store_dwordx2 v[186:187], v[164:165], off offset:1024 sc0 sc1
	global_store_dwordx2 v[186:187], v[160:161], off offset:1536 sc0 sc1
	s_and_saveexec_b64 s[18:19], s[0:1]
	s_cbranch_execz .LBB0_59
	global_load_dword v160, v[180:181], off
	v_mov_b32_e32 v162, s89
	v_mov_b32_e32 v163, s90
	v_pk_add_f32 v[162:163], s[56:57], v[162:163]
	s_nop 0
	v_add_f32_e32 v161, v162, v163
	v_mov_b32_e32 v162, s87
	v_mov_b32_e32 v163, s88
	v_pk_add_f32 v[162:163], s[54:55], v[162:163]
	s_nop 0
	v_add_f32_e32 v164, v162, v163
	v_mov_b32_e32 v162, s85
	v_mov_b32_e32 v163, s86
	v_pk_add_f32 v[162:163], s[48:49], v[162:163]
	s_nop 0
	v_add_f32_e32 v165, v162, v163
	v_mov_b32_e32 v162, s83
	v_mov_b32_e32 v163, s84
	v_pk_add_f32 v[162:163], s[42:43], v[162:163]
	s_nop 0
	v_add_f32_e32 v166, v162, v163
	v_mov_b32_e32 v162, s81
	v_mov_b32_e32 v163, s82
	v_pk_add_f32 v[162:163], s[40:41], v[162:163]
	s_nop 0
	v_add_f32_e32 v167, v162, v163
	v_mov_b32_e32 v162, s79
	v_mov_b32_e32 v163, s80
	v_pk_add_f32 v[162:163], s[30:31], v[162:163]
	s_nop 0
	v_add_f32_e32 v168, v162, v163
	v_mov_b32_e32 v162, s72
	v_mov_b32_e32 v163, s73
	v_pk_add_f32 v[162:163], s[28:29], v[162:163]
	s_nop 0
	v_add_f32_e32 v169, v162, v163
	v_mov_b32_e32 v162, s24
	v_mov_b32_e32 v163, s71
	v_pk_add_f32 v[162:163], s[26:27], v[162:163]
	s_nop 0
	v_add_f32_e32 v162, v162, v163
	v_cndmask_b32_e64 v162, v162, v169, s[16:17]
	v_cndmask_b32_e64 v162, v162, v168, s[4:5]
	v_cndmask_b32_e64 v162, v162, v167, s[6:7]
	v_cndmask_b32_e64 v162, v162, v166, s[8:9]
	v_cndmask_b32_e64 v162, v162, v165, s[10:11]
	v_cndmask_b32_e64 v162, v162, v164, s[12:13]
	v_cndmask_b32_e64 v161, v162, v161, s[14:15]
	s_waitcnt vmcnt(0)
	v_fmac_f32_e32 v160, v184, v161
	v_cmp_ngt_f32_e32 vcc, 0, v160
	s_and_saveexec_b64 s[26:27], vcc
	s_xor_b64 s[26:27], exec, s[26:27]
	s_cbranch_execz .LBB0_63
	v_mul_f32_e32 v161, 0xbfb8aa3b, v160
	v_rndne_f32_e32 v162, v161
	v_sub_f32_e32 v163, v161, v162
	v_fma_f32 v161, v160, s60, -v161
	v_fmac_f32_e32 v161, 0xb2a5705f, v160
	v_add_f32_e32 v161, v163, v161
	v_cvt_i32_f32_e32 v162, v162
	v_exp_f32_e32 v161, v161
	v_cmp_nlt_f32_e32 vcc, s61, v160
	v_ldexp_f32 v161, v161, v162
	s_nop 0
	v_cndmask_b32_e32 v161, 0, v161, vcc
	v_cmp_ngt_f32_e32 vcc, s62, v160
	s_nop 1
	v_cndmask_b32_e32 v174, v197, v161, vcc
	v_add_f32_e32 v162, 1.0, v174
	v_add_f32_e32 v160, -1.0, v162
	v_sub_f32_e32 v161, v160, v162
	v_add_f32_e32 v161, 1.0, v161
	v_sub_f32_e32 v160, v174, v160
	v_add_f32_e32 v163, v160, v161
	v_frexp_mant_f32_e32 v164, v162
	v_cvt_f64_f32_e32 v[160:161], v162
	v_frexp_exp_i32_f64_e32 v160, v[160:161]
	v_cmp_gt_f32_e32 vcc, s64, v164
	s_nop 1
	v_subbrev_co_u32_e32 v168, vcc, 0, v160, vcc
	v_sub_u32_e32 v160, 0, v168
	v_ldexp_f32 v161, v162, v160
	v_add_f32_e32 v162, -1.0, v161
	v_add_f32_e32 v164, 1.0, v161
	v_ldexp_f32 v160, v163, v160
	v_add_f32_e32 v163, 1.0, v162
	v_add_f32_e32 v165, -1.0, v164
	v_sub_f32_e32 v163, v161, v163
	v_sub_f32_e32 v161, v161, v165
	v_add_f32_e32 v163, v160, v163
	v_add_f32_e32 v160, v160, v161
	v_add_f32_e32 v169, v164, v160
	v_rcp_f32_e32 v171, v169
	v_sub_f32_e32 v161, v164, v169
	v_add_f32_e32 v170, v160, v161
	v_add_f32_e32 v161, v162, v163
	v_mul_f32_e32 v173, v161, v171
	v_sub_f32_e32 v160, v162, v161
	v_mul_f32_e32 v162, v169, v173
	v_fma_f32 v164, v173, v169, -v162
	v_fmac_f32_e32 v164, v173, v170
	v_add_f32_e32 v172, v163, v160
	v_add_f32_e32 v160, v162, v164
	v_sub_f32_e32 v163, v161, v160
	v_pk_add_f32 v[166:167], v[160:161], v[162:163] neg_lo:[0,1] neg_hi:[0,1]
	v_mov_b32_e32 v165, v160
	v_pk_add_f32 v[160:161], v[166:167], v[164:165] neg_lo:[0,1] neg_hi:[0,1]
	v_cmp_neq_f32_e32 vcc, s63, v174
	v_add_f32_e32 v161, v172, v161
	v_add_f32_e32 v160, v160, v161
	v_add_f32_e32 v161, v163, v160
	v_mul_f32_e32 v172, v171, v161
	v_mul_f32_e32 v162, v169, v172
	v_fma_f32 v164, v172, v169, -v162
	v_fmac_f32_e32 v164, v172, v170
	v_sub_f32_e32 v163, v163, v161
	v_add_f32_e32 v169, v160, v163
	v_add_f32_e32 v160, v162, v164
	v_sub_f32_e32 v163, v161, v160
	v_pk_add_f32 v[166:167], v[160:161], v[162:163] neg_lo:[0,1] neg_hi:[0,1]
	v_mov_b32_e32 v165, v160
	v_pk_add_f32 v[160:161], v[166:167], v[164:165] neg_lo:[0,1] neg_hi:[0,1]
	s_nop 0
	v_add_f32_e32 v161, v169, v161
	v_add_f32_e32 v160, v160, v161
	v_add_f32_e32 v161, v173, v172
	v_add_f32_e32 v160, v163, v160
	v_sub_f32_e32 v162, v161, v173
	v_mul_f32_e32 v160, v171, v160
	v_sub_f32_e32 v162, v172, v162
	v_add_f32_e32 v162, v162, v160
	v_add_f32_e32 v164, v161, v162
	v_mul_f32_e32 v165, v164, v164
	v_fmamk_f32 v160, v165, 0x3e9b6dac, v196
	v_fmaak_f32 v183, v165, v160, 0x3f2aaada
	v_cvt_f32_i32_e32 v160, v168
	v_sub_f32_e32 v161, v164, v161
	v_sub_f32_e32 v161, v162, v161
	v_ldexp_f32 v166, v161, 1
	v_mul_f32_e32 v161, v164, v165
	v_ldexp_f32 v163, v164, 1
	v_pk_mul_f32 v[164:165], v[160:161], v[182:183]
	s_nop 0
	v_fma_f32 v162, v160, s65, -v164
	v_fmac_f32_e32 v162, 0xb102e308, v160
	v_pk_add_f32 v[160:161], v[164:165], v[162:163]
	s_nop 0
	v_sub_f32_e32 v163, v161, v163
	v_sub_f32_e32 v163, v165, v163
	v_add_f32_e32 v167, v166, v163
	v_mov_b32_e32 v166, v164
	v_pk_add_f32 v[164:165], v[160:161], v[164:165] neg_lo:[0,1] neg_hi:[0,1]
	v_pk_add_f32 v[168:169], v[160:161], v[166:167]
	v_mov_b32_e32 v163, v160
	v_mov_b32_e32 v165, v169
	v_pk_add_f32 v[170:171], v[162:163], v[164:165] neg_lo:[0,1] neg_hi:[0,1]
	v_pk_add_f32 v[162:163], v[162:163], v[164:165]
	v_mov_b32_e32 v166, v167
	v_pk_add_f32 v[164:165], v[162:163], v[160:161] op_sel:[1,0] op_sel_hi:[0,1] neg_lo:[0,1] neg_hi:[0,1]
	v_pk_add_f32 v[172:173], v[168:169], v[164:165] op_sel_hi:[1,0] neg_lo:[0,1] neg_hi:[0,1]
	v_mov_b32_e32 v168, v169
	v_mov_b32_e32 v169, v163
	v_pk_mov_b32 v[164:165], v[160:161], v[164:165] op_sel:[1,0]
	v_mov_b32_e32 v167, v160
	v_pk_add_f32 v[164:165], v[168:169], v[164:165] neg_lo:[0,1] neg_hi:[0,1]
	v_mov_b32_e32 v172, v170
	v_pk_add_f32 v[160:161], v[166:167], v[164:165] neg_lo:[0,1] neg_hi:[0,1]
	v_mov_b32_e32 v171, v163
	v_pk_add_f32 v[164:165], v[172:173], v[160:161]
	s_nop 0
	v_pk_add_f32 v[166:167], v[164:165], v[164:165] op_sel:[0,1] op_sel_hi:[1,0]
	s_nop 0
	v_pk_add_f32 v[162:163], v[162:163], v[166:167] op_sel:[1,0] op_sel_hi:[0,1]
	v_mov_b32_e32 v165, v162
	v_pk_add_f32 v[168:169], v[164:165], v[170:171] neg_lo:[0,1] neg_hi:[0,1]
	v_mov_b32_e32 v161, v166
	v_sub_f32_e32 v163, v164, v168
	v_pk_add_f32 v[160:161], v[160:161], v[168:169] neg_lo:[0,1] neg_hi:[0,1]
	v_sub_f32_e32 v163, v170, v163
	v_add_f32_e32 v160, v160, v163
	v_add_f32_e32 v160, v160, v161
	v_add_f32_e32 v160, v162, v160
	v_cndmask_b32_e32 v160, v197, v160, vcc
	v_cmp_lt_f32_e64 vcc, |v174|, s66
	s_nop 1
	v_cndmask_b32_e32 v160, v160, v174, vcc
	v_xor_b32_e32 v161, 0x80000000, v160

.LBB0_73:
	s_or_b64 exec, exec, s[4:5]
	s_bitcmp1_b32 s99, 2
	s_cbranch_scc0 .Lp0_chk_rows
	s_waitcnt lgkmcnt(0)
	s_barrier
	v_readlane_b32 s27, v255, 0
	v_readlane_b32 s54, v255, 1
	v_readlane_b32 s55, v255, 2
	s_add_u32 s40, s76, 0x7c00000
	s_addc_u32 s41, s77, 0
	s_bitcmp1_b32 s99, 6
	s_cbranch_scc1 .Lp0_ret_rows
	s_bitcmp1_b32 s99, 3
	s_cbranch_scc1 .Lp0_retx
	s_andn2_b32 s99, s99, 12
	s_branch .Lp2_prologue

.Lp0_ret_rows:
	s_andn2_b32 s99, s99, 0x4c
	s_branch .Lrows_call
.Lp0_chk_rows:
	s_bitcmp1_b32 s99, 7
	s_cbranch_scc0 .Lg0_entry
	s_andn2_b32 s99, s99, 0x80
	s_bitcmp1_b32 s99, 0
	s_cbranch_scc0 .Ll1_global
	s_waitcnt vmcnt(0) lgkmcnt(0)
	s_barrier
	s_cmp_lg_u32 s33, 0
	s_cbranch_scc1 .Lls_join_0
	s_mov_b64 exec, 1
	s_add_i32 s98, 0, 0x25fd0
	v_mov_b32_e32 v0, s98
	ds_read_b32 v2, v0
	s_getreg_b32 s98, hwreg(HW_REG_XCC_ID, 0, 4)
	s_and_b32 s98, s98, 15
	s_lshl_b32 s98, s98, 8
	s_add_u32 s100, s76, s98
	s_addc_u32 s101, s77, 0
	v_mov_b32_e32 v0, 0xc000
	v_mov_b32_e32 v1, 1
	global_atomic_add v0, v1, s[100:101]
	s_waitcnt lgkmcnt(0)
	s_mov_b32 s98, 0

.Lls_join_0:
	v_readlane_b32 s27, v255, 0
	s_mov_b32 s98, 1
	s_barrier
	s_branch .Lp1_go
.Ll1_global:
	s_mov_b32 s98, 2

.LBB0_126:
	s_cmp_eq_u32 s98, 0
	s_cbranch_scc0 .Lp1_go
	s_mov_b32 s99, 0
	s_cmp_lg_u32 s3, 0x100
	s_cbranch_scc1 .Lflag_done
	v_mbcnt_lo_u32_b32 v0, -1, 0
	v_mbcnt_hi_u32_b32 v0, -1, v0
	v_lshlrev_b32_e32 v1, 4, v0
	v_add_u32_e32 v1, 0xe000, v1
	global_load_dwordx4 v[4:7], v1, s[76:77]
	v_and_b32_e32 v2, 1, v0
	s_waitcnt vmcnt(0)
	v_readlane_b32 s4, v4, 0
	v_readlane_b32 s5, v5, 0
	v_readlane_b32 s6, v6, 0
	v_readlane_b32 s7, v7, 0
	v_readlane_b32 s8, v4, 1
	v_readlane_b32 s9, v5, 1
	v_readlane_b32 s10, v6, 1
	v_readlane_b32 s11, v7, 1
	v_cmp_eq_u32_e32 vcc, 1, v2
	v_mov_b32_e32 v8, s4
	v_mov_b32_e32 v9, s8
	v_cndmask_b32_e32 v8, v8, v9, vcc
	v_mov_b32_e32 v10, s5
	v_mov_b32_e32 v9, s9
	v_cndmask_b32_e32 v10, v10, v9, vcc
	v_mov_b32_e32 v11, s6
	v_mov_b32_e32 v9, s10
	v_cndmask_b32_e32 v11, v11, v9, vcc
	v_mov_b32_e32 v12, s7
	v_mov_b32_e32 v9, s11
	v_cndmask_b32_e32 v12, v12, v9, vcc
	v_xor_b32_e32 v8, v4, v8
	v_xor_b32_e32 v10, v5, v10
	v_xor_b32_e32 v11, v6, v11
	v_xor_b32_e32 v12, v7, v12
	v_or3_b32 v8, v8, v10, v11
	v_or_b32_e32 v8, v8, v12
	v_min_u32_e32 v9, v4, v5
	v_min3_u32 v9, v9, v6, v7
	v_cmp_ne_u32_e32 vcc, 0, v8
	v_cmp_eq_u32_e64 s[4:5], 0, v9
	s_nop 3
	s_or_b64 s[4:5], vcc, s[4:5]
	s_cmp_lg_u64 s[4:5], 0
	s_cbranch_scc1 .Lflag_done
	s_mov_b32 s99, 1
	s_bitcmp1_b32 s2, 2
	s_cbranch_scc0 .Lflag_done
	s_or_b32 s99, s99, 16
.Lflag_done:
	s_mov_b32 s98, 1
	s_bitcmp1_b32 s2, 2
	s_cbranch_scc0 .Lrows_call
	s_or_b32 s99, s99, 0x44
	s_branch .Lp0b_call
.Lrows_call:
	s_or_b32 s99, s99, 0x80
	s_branch .Lp0b_call

.LBB0_256:
	s_mov_b32 s98, 0
	s_bitcmp1_b32 s2, 2
	s_cbranch_scc0 .Lp2i_done
	s_movk_i32 s98, 0x1000

.Lp0b_ret_exit:
	s_cmp_eq_u32 s99, 0
	s_cbranch_scc1 .Lfull_2
	v_readlane_b32 s54, v255, 1
	v_readlane_b32 s27, v255, 0
	v_readlane_b32 s55, v255, 2
	s_waitcnt vmcnt(0) lgkmcnt(0)
	s_barrier
	s_cmp_lg_u32 s33, 0
	s_cbranch_scc1 .Lls_join_2
	s_mov_b64 exec, 1
	s_add_i32 s98, 0, 0x25fd0
	v_mov_b32_e32 v0, s98
	ds_read_b32 v2, v0
	s_getreg_b32 s98, hwreg(HW_REG_XCC_ID, 0, 4)
	s_and_b32 s98, s98, 15
	s_lshl_b32 s98, s98, 8
	s_add_u32 s100, s76, s98
	s_addc_u32 s101, s77, 0
	v_mov_b32_e32 v0, 0xc000
	v_mov_b32_e32 v1, 1
	global_atomic_add v0, v1, s[100:101]
	s_waitcnt lgkmcnt(0)
	v_mul_lo_u32 v2, v2, 3
	s_mov_b32 s98, 0
